# up-projection: q tiles start where the kv tiles of the workgroup end (one combined tile queue per XCD: at most 3 tiles per workgroup); in-proj -> up-proj seam XCD-local on even layers
# speedup vs baseline: 1.0161x; 1.0061x over previous
.Lhw_bar_scope:
	v_readlane_b32 s2, v246, 26
	s_and_b32 s9, s88, 1
	s_lshl_b32 s8, s9, 8
	s_xor_b32 s9, s9, 1
	s_lshl_b32 s9, s9, 6
	s_or_b32 s8, s8, s9
	s_or_b32 s8, s8, 0xe1e
	s_lshr_b32 s8, s8, s2
	v_readlane_b32 s6, v246, 41
	s_and_b32 s8, s8, 1
	s_and_b32 s8, s8, s6
	v_writelane_b32 v246, s8, 42
	s_waitcnt vmcnt(0)
	s_barrier
	v_mov_b32 v0, v194
	s_nop 0
	v_cmp_eq_u32_e32 vcc, 0, v0
	s_and_saveexec_b64 s[0:1], vcc
	s_cbranch_execz .LBB0_108
	s_waitcnt vmcnt(0) expcnt(0) lgkmcnt(0)
	ds_read_b32 v3, v1
	ds_read_b32 v0, v1 offset:4
	s_waitcnt lgkmcnt(1)
	v_cmp_ne_u32_e32 vcc, 0, v3
	s_cbranch_vccnz .LBB0_71
	s_mov_b32 s2, 1
	s_branch .LBB0_54

.LBB0_1148:
	v_readlane_b32 s8, v247, 25
	v_readlane_b32 s9, v247, 26
	s_andn2_b64 vcc, exec, s[8:9]
	s_cbranch_vccnz .LBB0_1287
	s_load_dwordx2 s[8:9], s[54:55], 0x88
	s_waitcnt lgkmcnt(0)
	s_add_u32 s46, s52, 0x16158100
	s_mul_i32 s2, s0, 0x600
	s_addc_u32 s47, s53, 0
	s_mul_hi_i32 s1, s0, 0x600
	s_add_u32 s48, s8, s2
	s_mul_i32 s10, s0, 0x90000
	s_addc_u32 s49, s9, s1
	s_mul_hi_i32 s6, s0, 0x90000
	s_add_u32 s1, s52, s10
	s_addc_u32 s2, s53, s6
	s_add_u32 s50, s1, 0x10978100
	s_addc_u32 s51, s2, 0
	s_add_u32 s54, s52, 0x17058100
	s_addc_u32 s55, s53, 0
	s_add_u32 s52, s52, 0x16158120
	s_addc_u32 s53, s53, 0
	s_add_i32 s1, s83, 16
	s_sub_i32 s2, s83, 48
	s_cmpk_lt_u32 s83, 48
	s_cselect_b32 s1, s1, s2
	s_branch .LBB0_1151
